# grid-barrier spin loops sleep 1 instead of 6 between polls; on v61
# speedup vs baseline: 1.0168x; 1.0168x over previous
; __device__ __forceinline__ unsigned xb_ld(unsigned* p)              { return __hip_atomic_load(p, __ATOMIC_RELAXED, __HIP_MEMORY_SCOPE_AGENT); }
; __device__ __forceinline__ void xcd_barrier_complete(unsigned* bar, unsigned x, unsigned& nloc, unsigned& nx) {
;     ...
;     for (;;) {
;         sum = 0u; cnt = 0u; mine = 0u;
; #pragma unroll
;         for (unsigned j = 0; j < 16; ++j) { const unsigned c = xb_ld(&bar[XB_XCNT(j)]); sum += c; cnt += (c > 0u) ? 1u : 0u; mine = (j == x) ? c : mine; }
;         if (sum == G) break;
;         __builtin_amdgcn_s_sleep(6);
;         if ((++sp & 255u) == 0u) { if (xb_ld(&bar[XB_TMO])) break; if (sp > XB_SPIN_CAP) { atomicAdd(&bar[XB_TMO], 1u); break; } }
;     }
.LBB0_94:
	global_load_dword v51, v[4:5], off sc1
	global_load_dword v49, v[6:7], off sc1
	global_load_dword v50, v[8:9], off sc1
	global_load_dword v47, v[10:11], off sc1
	global_load_dword v48, v[12:13], off sc1
	global_load_dword v45, v[14:15], off sc1
	global_load_dword v46, v[16:17], off sc1
	global_load_dword v43, v[18:19], off sc1
	global_load_dword v44, v[20:21], off sc1
	global_load_dword v41, v[22:23], off sc1
	global_load_dword v42, v[24:25], off sc1
	global_load_dword v39, v[26:27], off sc1
	global_load_dword v40, v[28:29], off sc1
	global_load_dword v37, v[30:31], off sc1
	global_load_dword v38, v[32:33], off sc1
	global_load_dword v36, v[34:35], off sc1
	s_or_b64 s[10:11], s[10:11], exec
	s_or_b64 s[8:9], s[8:9], exec
	s_waitcnt vmcnt(14)
	v_add_u32_e32 v52, v49, v51
	s_waitcnt vmcnt(12)
	v_add3_u32 v52, v52, v50, v47
	s_waitcnt vmcnt(10)
	v_add3_u32 v52, v52, v48, v45
	s_waitcnt vmcnt(8)
	v_add3_u32 v52, v52, v46, v43
	s_waitcnt vmcnt(6)
	v_add3_u32 v52, v52, v44, v41
	s_waitcnt vmcnt(4)
	v_add3_u32 v52, v52, v42, v39
	s_waitcnt vmcnt(2)
	v_add3_u32 v52, v52, v40, v37
	s_waitcnt vmcnt(0)
	v_add3_u32 v52, v52, v38, v36
	v_cmp_ne_u32_e32 vcc, s24, v52
	s_and_saveexec_b64 s[14:15], vcc
	s_cbranch_execz .LBB0_93
	s_and_b32 s18, s25, 0xff
	s_mov_b64 s[16:17], -1
	s_cmp_eq_u32 s18, 0
	s_mov_b64 s[20:21], -1
	s_mov_b64 s[18:19], -1
	s_sleep 1
	s_cbranch_scc1 .LBB0_97
	s_and_saveexec_b64 s[22:23], s[20:21]
	s_cbranch_execz .LBB0_92
	s_branch .LBB0_100

.LBB0_108:
	s_and_b32 s18, s13, 0xff
	s_mov_b64 s[16:17], -1
	s_cmp_lg_u32 s18, 0
	s_mov_b64 s[18:19], -1
	s_sleep 1
	s_cbranch_scc1 .LBB0_112
	global_load_dword v4, v[0:1], off sc1
	s_mov_b64 s[18:19], 0
	s_mov_b64 s[20:21], -1
	s_waitcnt vmcnt(0)
	v_cmp_eq_u32_e32 vcc, 0, v4
	s_and_saveexec_b64 s[22:23], vcc
	s_cmp_lt_u32 s13, 0x20001
	s_cselect_b64 s[18:19], -1, 0
	s_xor_b64 s[20:21], exec, -1
	s_and_b64 s[18:19], s[18:19], exec
	s_or_b64 exec, exec, s[22:23]

.LBB0_122:
	s_and_b32 s14, s13, 0xff
	s_cmp_lg_u32 s14, 0
	s_mov_b64 s[16:17], -1
	s_sleep 1
	s_cbranch_scc0 .LBB0_124
	s_mov_b64 s[18:19], -1
	s_and_saveexec_b64 s[20:21], s[16:17]
	s_cbranch_execz .LBB0_121
	s_branch .LBB0_127

; __device__ __forceinline__ unsigned xb_ld(unsigned* p)              { return __hip_atomic_load(p, __ATOMIC_RELAXED, __HIP_MEMORY_SCOPE_AGENT); }
; __device__ __forceinline__ void xcd_barrier_complete(unsigned* bar, unsigned x, unsigned& nloc, unsigned& nx) {
;     ...
;     for (;;) {
;         sum = 0u; cnt = 0u; mine = 0u;
; #pragma unroll
;         for (unsigned j = 0; j < 16; ++j) { const unsigned c = xb_ld(&bar[XB_XCNT(j)]); sum += c; cnt += (c > 0u) ? 1u : 0u; mine = (j == x) ? c : mine; }
;         if (sum == G) break;
;         __builtin_amdgcn_s_sleep(6);
;         if ((++sp & 255u) == 0u) { if (xb_ld(&bar[XB_TMO])) break; if (sp > XB_SPIN_CAP) { atomicAdd(&bar[XB_TMO], 1u); break; } }
;     }
.LBB0_284:
	global_load_dword v51, v[4:5], off sc1
	global_load_dword v49, v[6:7], off sc1
	global_load_dword v50, v[8:9], off sc1
	global_load_dword v47, v[10:11], off sc1
	global_load_dword v48, v[12:13], off sc1
	global_load_dword v45, v[14:15], off sc1
	global_load_dword v46, v[16:17], off sc1
	global_load_dword v43, v[18:19], off sc1
	global_load_dword v44, v[20:21], off sc1
	global_load_dword v41, v[22:23], off sc1
	global_load_dword v42, v[24:25], off sc1
	global_load_dword v39, v[26:27], off sc1
	global_load_dword v40, v[28:29], off sc1
	global_load_dword v37, v[30:31], off sc1
	global_load_dword v38, v[32:33], off sc1
	global_load_dword v36, v[34:35], off sc1
	s_or_b64 s[10:11], s[10:11], exec
	s_or_b64 s[8:9], s[8:9], exec
	s_waitcnt vmcnt(14)
	v_add_u32_e32 v52, v49, v51
	s_waitcnt vmcnt(12)
	v_add3_u32 v52, v52, v50, v47
	s_waitcnt vmcnt(10)
	v_add3_u32 v52, v52, v48, v45
	s_waitcnt vmcnt(8)
	v_add3_u32 v52, v52, v46, v43
	s_waitcnt vmcnt(6)
	v_add3_u32 v52, v52, v44, v41
	s_waitcnt vmcnt(4)
	v_add3_u32 v52, v52, v42, v39
	s_waitcnt vmcnt(2)
	v_add3_u32 v52, v52, v40, v37
	s_waitcnt vmcnt(0)
	v_add3_u32 v52, v52, v38, v36
	v_cmp_ne_u32_e32 vcc, s33, v52
	s_and_saveexec_b64 s[14:15], vcc
	s_cbranch_execz .LBB0_283
	s_and_b32 s18, s24, 0xff
	s_mov_b64 s[16:17], -1
	s_cmp_eq_u32 s18, 0
	s_mov_b64 s[20:21], -1
	s_mov_b64 s[18:19], -1
	s_sleep 1
	s_cbranch_scc1 .LBB0_287
	s_and_saveexec_b64 s[22:23], s[20:21]
	s_cbranch_execz .LBB0_282
	s_branch .LBB0_290

.LBB0_298:
	s_and_b32 s18, s24, 0xff
	s_mov_b64 s[16:17], -1
	s_cmp_lg_u32 s18, 0
	s_mov_b64 s[18:19], -1
	s_sleep 1
	s_cbranch_scc1 .LBB0_302
	global_load_dword v4, v[0:1], off sc1
	s_mov_b64 s[18:19], 0
	s_mov_b64 s[20:21], -1
	s_waitcnt vmcnt(0)
	v_cmp_eq_u32_e32 vcc, 0, v4
	s_and_saveexec_b64 s[22:23], vcc
	s_cmp_lt_u32 s24, 0x20001
	s_cselect_b64 s[18:19], -1, 0
	s_xor_b64 s[20:21], exec, -1
	s_and_b64 s[18:19], s[18:19], exec
	s_or_b64 exec, exec, s[22:23]

.LBB0_312:
	s_and_b32 s16, s22, 0xff
	s_mov_b64 s[14:15], -1
	s_cmp_lg_u32 s16, 0
	s_mov_b64 s[18:19], -1
	s_sleep 1
	s_cbranch_scc0 .LBB0_314
	s_and_saveexec_b64 s[20:21], s[18:19]
	s_cbranch_execz .LBB0_311
	s_branch .LBB0_317
